# v44 + P0 weight-copy LDS bank-conflict fix (per-wave rotation of the staged 16-byte pieces on the DMA source, un-rotated by the column readers: 8-way conflict -> conflict-free)
# baseline (speedup 1.0000x reference)
.LBB0_59:
	s_lshl_b32 s11, s62, 3
	s_mov_b32 m0, s33
	s_or_b32 s33, s11, 1
	s_or_b32 s35, s11, 2
	s_or_b32 s56, s11, 3
	s_or_b32 s57, s11, 4
	s_or_b32 s59, s11, 5
	s_or_b32 s61, s11, 6
	s_or_b32 s64, s11, 7
	s_add_u32 s12, s54, 0x500000
	s_addc_u32 s13, s55, 0
	s_add_u32 s14, s54, 0x2300000
	s_addc_u32 s15, s55, 0
	s_add_u32 s38, s54, 0x1b00000
	s_addc_u32 s39, s55, 0
	s_add_u32 s42, s54, 0x1900000
	s_addc_u32 s43, s55, 0
	s_add_u32 s66, s54, 0x1500000
	s_addc_u32 s67, s55, 0
	s_add_i32 s7, s65, s11
	s_mul_i32 s69, s5, s7
	s_mul_hi_u32 s70, s4, s7
	s_add_i32 s71, s70, s69
	s_mul_i32 s70, s4, s7
	s_lshl_b64 s[70:71], s[70:71], 2
	s_add_u32 s69, s0, s70
	s_addc_u32 s71, s1, s71
	s_ashr_i32 s7, s6, 31
	s_lshl_b64 s[6:7], s[6:7], 2
	v_ashrrev_i32_e32 v89, 31, v88
	s_add_u32 s70, s69, s6
	s_addc_u32 s71, s71, s7
	v_add_u32_e32 v0, s62, v92
	v_and_b32_e32 v0, 63, v0
	v_lshlrev_b32_e32 v0, 4, v0
	v_mov_b32_e32 v1, 0
	s_add_i32 s69, s65, s33
	v_lshl_add_u64 v[2:3], s[70:71], 0, v[0:1]
	s_mul_i32 s70, s5, s69
	s_mul_hi_u32 s71, s4, s69
	s_add_i32 s71, s71, s70
	s_mul_i32 s70, s4, s69
	s_lshl_b64 s[70:71], s[70:71], 2
	s_add_u32 s69, s0, s70
	s_addc_u32 s71, s1, s71
	s_add_u32 s70, s69, s6
	s_addc_u32 s71, s71, s7
	global_load_lds_dwordx4 v[2:3], off nt
	v_lshl_add_u64 v[2:3], s[70:71], 0, v[0:1]
	s_add_i32 s70, s65, s35
	s_mul_i32 s71, s5, s70
	s_mul_hi_u32 s72, s4, s70
	s_mul_i32 s34, s33, 0x410
	s_add_i32 s71, s72, s71
	s_mul_i32 s70, s4, s70
	s_add_i32 s69, s34, 0
	s_lshl_b64 s[70:71], s[70:71], 2
	s_add_u32 s70, s0, s70
	s_addc_u32 s71, s1, s71
	s_add_u32 s70, s70, s6
	s_mov_b32 m0, s69
	s_addc_u32 s71, s71, s7
	global_load_lds_dwordx4 v[2:3], off nt
	v_lshl_add_u64 v[2:3], s[70:71], 0, v[0:1]
	s_add_i32 s70, s65, s56
	s_mul_i32 s71, s5, s70
	s_mul_hi_u32 s72, s4, s70
	s_add_i32 s71, s72, s71
	s_mul_i32 s70, s4, s70
	s_add_i32 m0, s69, 0x410
	s_lshl_b64 s[70:71], s[70:71], 2
	s_add_u32 s70, s0, s70
	s_addc_u32 s71, s1, s71
	s_add_u32 s70, s70, s6
	s_addc_u32 s71, s71, s7
	global_load_lds_dwordx4 v[2:3], off nt
	v_lshl_add_u64 v[2:3], s[70:71], 0, v[0:1]
	s_add_i32 s70, s65, s57
	s_mul_i32 s71, s5, s70
	s_mul_hi_u32 s72, s4, s70
	s_add_i32 s71, s72, s71
	s_mul_i32 s70, s4, s70
	s_add_i32 m0, s69, 0x820
	s_lshl_b64 s[70:71], s[70:71], 2
	s_add_u32 s70, s0, s70
	s_addc_u32 s71, s1, s71
	s_add_u32 s70, s70, s6
	s_addc_u32 s71, s71, s7
	global_load_lds_dwordx4 v[2:3], off nt
	v_lshl_add_u64 v[2:3], s[70:71], 0, v[0:1]
	s_add_i32 s70, s65, s59
	s_mul_i32 s71, s5, s70
	s_mul_hi_u32 s72, s4, s70
	s_add_i32 s71, s72, s71
	s_mul_i32 s70, s4, s70
	s_add_i32 m0, s69, 0xc30
	s_lshl_b64 s[70:71], s[70:71], 2
	s_add_u32 s70, s0, s70
	s_addc_u32 s71, s1, s71
	s_add_u32 s70, s70, s6
	s_addc_u32 s71, s71, s7
	global_load_lds_dwordx4 v[2:3], off nt
	v_lshl_add_u64 v[2:3], s[70:71], 0, v[0:1]
	s_add_i32 s70, s65, s61
	s_mul_i32 s71, s5, s70
	s_mul_hi_u32 s72, s4, s70
	s_add_i32 s71, s72, s71
	s_mul_i32 s70, s4, s70
	s_add_i32 m0, s69, 0x1040
	s_lshl_b64 s[70:71], s[70:71], 2
	s_add_u32 s70, s0, s70
	s_addc_u32 s71, s1, s71
	s_add_u32 s70, s70, s6
	s_addc_u32 s71, s71, s7
	s_add_i32 s65, s65, s64
	global_load_lds_dwordx4 v[2:3], off nt
	v_lshl_add_u64 v[2:3], s[70:71], 0, v[0:1]
	s_mul_i32 s5, s5, s65
	s_mul_hi_u32 s70, s4, s65
	s_add_i32 s5, s70, s5
	s_mul_i32 s4, s4, s65
	s_add_i32 m0, s69, 0x1450
	s_lshl_b64 s[4:5], s[4:5], 2
	s_add_u32 s0, s0, s4
	s_addc_u32 s1, s1, s5
	s_add_u32 s0, s0, s6
	s_addc_u32 s1, s1, s7
	global_load_lds_dwordx4 v[2:3], off nt
	v_lshl_add_u64 v[2:3], s[0:1], 0, v[0:1]
	s_add_i32 m0, s69, 0x1860
	v_and_b32_e32 v6, 7, v92
	global_load_lds_dwordx4 v[2:3], off nt
	v_ashrrev_i32_e32 v2, 3, v91
	v_lshlrev_b32_e32 v5, 1, v2
	v_add_u32_e32 v8, 64, v2
	v_add_u32_e32 v13, 0xc0, v2
	v_and_b32_e32 v18, 0x78, v5
	v_and_b32_e32 v7, 0x7b, v2
	v_lshrrev_b32_e32 v16, 4, v2
	v_and_b32_e32 v10, 0x7b, v8
	v_lshrrev_b32_e32 v17, 4, v8
	v_add_u32_e32 v11, 0x80, v2
	v_and_b32_e32 v15, 0x7b, v13
	v_lshrrev_b32_e32 v19, 4, v13
	s_lshl_b32 s0, s8, 2
	s_mov_b32 s65, 0
	v_lshlrev_b32_e32 v3, 4, v6
	v_bfe_u32 v4, v2, 2, 1
	v_lshlrev_b32_e32 v5, 2, v2
	v_mul_u32_u24_e32 v6, 0x2080, v6
	v_or_b32_e32 v7, 0x1000, v7
	v_lshlrev_b32_e32 v9, 2, v8
	v_or_b32_e32 v10, 0x1000, v10
	v_lshlrev_b32_e32 v12, 2, v11
	v_lshlrev_b32_e32 v14, 2, v13
	v_lshrrev_b32_e32 v252, 2, v2
	v_and_b32_e32 v253, 7, v92
	v_sub_u32_e32 v252, v252, v253
	v_and_b32_e32 v254, 3, v2
	v_lshlrev_b32_e32 v254, 2, v254
	v_and_b32_e32 v255, 63, v252
	v_lshl_or_b32 v5, v255, 4, v254
	v_add_u32_e32 v255, 16, v252
	v_and_b32_e32 v255, 63, v255
	v_lshl_or_b32 v9, v255, 4, v254
	v_add_u32_e32 v255, 32, v252
	v_and_b32_e32 v255, 63, v255
	v_lshl_or_b32 v12, v255, 4, v254
	v_add_u32_e32 v255, 48, v252
	v_and_b32_e32 v255, 63, v255
	v_lshl_or_b32 v14, v255, 4, v254
	v_or_b32_e32 v15, 0x1000, v15
	v_and_or_b32 v16, v16, 4, v18
	v_and_or_b32 v17, v17, 4, v18
	v_and_or_b32 v18, v19, 4, v18
	s_add_i32 s76, s0, 0x7ffff100
	s_add_i32 s77, s68, 0x7fffd400
	s_movk_i32 s78, 0x3ff
	s_movk_i32 s79, 0xbff
	s_movk_i32 s80, 0x1c00
	s_movk_i32 s81, 0xff83
	s_mov_b32 s7, 0x20000
	s_branch .LBB0_62
